# L1 gate bias folded into an fma with a pre-scaled LDS table (same math, one rounding fewer)
# speedup vs baseline: 1.0783x; 1.0005x over previous
.LBB0_298:
	s_or_b64 exec, exec, s[10:11]
	s_waitcnt vmcnt(0)
	v_add_u32_e32 v4, 0xfffff600, v2
	v_mov_b32_e32 v5, 0xbfb8aa3b
	v_cmp_gt_u32_e32 vcc, 0x800, v4
	s_nop 1
	v_cndmask_b32_e32 v4, 1.0, v5, vcc
	v_mul_f32_e32 v3, v3, v4
	ds_write_b32 v0, v3
	v_add_u32_e32 v3, 0x200, v2
	v_cmp_lt_i32_e32 vcc, s22, v2
	v_add_u32_e32 v0, 0x800, v0
	s_or_b64 s[8:9], vcc, s[8:9]
	v_mov_b32_e32 v2, v3
	s_andn2_b64 exec, exec, s[8:9]
	s_cbranch_execz .LBB0_321

.Lconv_nomask:
	v_lshlrev_b32_e32 v18, 16, v126
	v_and_b32_e32 v19, 0xffff0000, v126
	v_lshlrev_b32_e32 v20, 16, v127
	v_and_b32_e32 v21, 0xffff0000, v127
	v_lshlrev_b32_e32 v22, 16, v128
	v_and_b32_e32 v23, 0xffff0000, v128
	v_lshlrev_b32_e32 v24, 16, v129
	v_and_b32_e32 v25, 0xffff0000, v129
	v_lshlrev_b32_e32 v26, 16, v110
	v_and_b32_e32 v27, 0xffff0000, v110
	v_lshlrev_b32_e32 v28, 16, v111
	v_and_b32_e32 v29, 0xffff0000, v111
	v_lshlrev_b32_e32 v30, 16, v112
	v_and_b32_e32 v31, 0xffff0000, v112
	v_lshlrev_b32_e32 v32, 16, v113
	v_and_b32_e32 v33, 0xffff0000, v113
	s_waitcnt lgkmcnt(4)
	v_pk_fma_f32 v[2:3], v[144:145], v[18:19], v[2:3]
	v_pk_fma_f32 v[4:5], v[146:147], v[20:21], v[4:5]
	v_pk_fma_f32 v[6:7], v[148:149], v[22:23], v[6:7]
	v_pk_fma_f32 v[8:9], v[150:151], v[24:25], v[8:9]
	v_pk_fma_f32 v[14:15], v[152:153], v[26:27], v[14:15]
	v_pk_fma_f32 v[16:17], v[154:155], v[28:29], v[16:17]
	v_pk_fma_f32 v[10:11], v[156:157], v[30:31], v[10:11]
	v_pk_fma_f32 v[12:13], v[158:159], v[32:33], v[12:13]
	ds_read_b128 v[144:147], v188 offset:4096
	ds_read_b128 v[148:151], v188 offset:4112
	ds_read_b128 v[152:155], v196 offset:4096
	ds_read_b128 v[156:159], v196 offset:4112
	v_lshlrev_b32_e32 v18, 16, v122
	v_and_b32_e32 v19, 0xffff0000, v122
	v_lshlrev_b32_e32 v20, 16, v123
	v_and_b32_e32 v21, 0xffff0000, v123
	v_lshlrev_b32_e32 v22, 16, v124
	v_and_b32_e32 v23, 0xffff0000, v124
	v_lshlrev_b32_e32 v24, 16, v125
	v_and_b32_e32 v25, 0xffff0000, v125
	v_lshlrev_b32_e32 v26, 16, v106
	v_and_b32_e32 v27, 0xffff0000, v106
	v_lshlrev_b32_e32 v28, 16, v107
	v_and_b32_e32 v29, 0xffff0000, v107
	v_lshlrev_b32_e32 v30, 16, v108
	v_and_b32_e32 v31, 0xffff0000, v108
	v_lshlrev_b32_e32 v32, 16, v109
	v_and_b32_e32 v33, 0xffff0000, v109
	s_waitcnt lgkmcnt(4)
	v_pk_fma_f32 v[2:3], v[160:161], v[18:19], v[2:3]
	v_pk_fma_f32 v[4:5], v[162:163], v[20:21], v[4:5]
	v_pk_fma_f32 v[6:7], v[164:165], v[22:23], v[6:7]
	v_pk_fma_f32 v[8:9], v[166:167], v[24:25], v[8:9]
	v_pk_fma_f32 v[14:15], v[130:131], v[26:27], v[14:15]
	v_pk_fma_f32 v[16:17], v[132:133], v[28:29], v[16:17]
	v_pk_fma_f32 v[10:11], v[134:135], v[30:31], v[10:11]
	v_pk_fma_f32 v[12:13], v[136:137], v[32:33], v[12:13]
	ds_read_b128 v[160:163], v188 offset:6144
	ds_read_b128 v[164:167], v188 offset:6160
	ds_read_b128 v[130:133], v196 offset:6144
	ds_read_b128 v[134:137], v196 offset:6160
	v_lshlrev_b32_e32 v18, 16, v118
	v_and_b32_e32 v19, 0xffff0000, v118
	v_lshlrev_b32_e32 v20, 16, v119
	v_and_b32_e32 v21, 0xffff0000, v119
	v_lshlrev_b32_e32 v22, 16, v120
	v_and_b32_e32 v23, 0xffff0000, v120
	v_lshlrev_b32_e32 v24, 16, v121
	v_and_b32_e32 v25, 0xffff0000, v121
	v_lshlrev_b32_e32 v26, 16, v102
	v_and_b32_e32 v27, 0xffff0000, v102
	v_lshlrev_b32_e32 v28, 16, v103
	v_and_b32_e32 v29, 0xffff0000, v103
	v_lshlrev_b32_e32 v30, 16, v104
	v_and_b32_e32 v31, 0xffff0000, v104
	v_lshlrev_b32_e32 v32, 16, v105
	v_and_b32_e32 v33, 0xffff0000, v105
	s_waitcnt lgkmcnt(4)
	v_pk_fma_f32 v[2:3], v[144:145], v[18:19], v[2:3]
	v_pk_fma_f32 v[4:5], v[146:147], v[20:21], v[4:5]
	v_pk_fma_f32 v[6:7], v[148:149], v[22:23], v[6:7]
	v_pk_fma_f32 v[8:9], v[150:151], v[24:25], v[8:9]
	v_pk_fma_f32 v[14:15], v[152:153], v[26:27], v[14:15]
	v_pk_fma_f32 v[16:17], v[154:155], v[28:29], v[16:17]
	v_pk_fma_f32 v[10:11], v[156:157], v[30:31], v[10:11]
	v_pk_fma_f32 v[12:13], v[158:159], v[32:33], v[12:13]
	v_lshlrev_b32_e32 v18, 16, v114
	v_and_b32_e32 v19, 0xffff0000, v114
	v_lshlrev_b32_e32 v20, 16, v115
	v_and_b32_e32 v21, 0xffff0000, v115
	v_lshlrev_b32_e32 v22, 16, v116
	v_and_b32_e32 v23, 0xffff0000, v116
	v_lshlrev_b32_e32 v24, 16, v117
	v_and_b32_e32 v25, 0xffff0000, v117
	v_lshlrev_b32_e32 v26, 16, v98
	v_and_b32_e32 v27, 0xffff0000, v98
	v_lshlrev_b32_e32 v28, 16, v99
	v_and_b32_e32 v29, 0xffff0000, v99
	v_lshlrev_b32_e32 v30, 16, v100
	v_and_b32_e32 v31, 0xffff0000, v100
	v_lshlrev_b32_e32 v32, 16, v101
	v_and_b32_e32 v33, 0xffff0000, v101
	s_waitcnt lgkmcnt(0)
	v_pk_fma_f32 v[2:3], v[160:161], v[18:19], v[2:3]
	v_pk_fma_f32 v[4:5], v[162:163], v[20:21], v[4:5]
	v_pk_fma_f32 v[6:7], v[164:165], v[22:23], v[6:7]
	v_pk_fma_f32 v[8:9], v[166:167], v[24:25], v[8:9]
	v_pk_fma_f32 v[14:15], v[130:131], v[26:27], v[14:15]
	v_pk_fma_f32 v[16:17], v[132:133], v[28:29], v[16:17]
	v_pk_fma_f32 v[10:11], v[134:135], v[30:31], v[10:11]
	v_pk_fma_f32 v[12:13], v[136:137], v[32:33], v[12:13]
	v_cvt_pk_bf16_f32 v134, v2, v3
	v_cvt_pk_bf16_f32 v135, v4, v5
	v_cvt_pk_bf16_f32 v136, v6, v7
	ds_write_b128 v212, v[2:5]
	ds_write_b128 v212, v[6:9] offset:16
	ds_write_b128 v212, v[14:17] offset:128
	ds_write_b128 v212, v[10:13] offset:144
	s_waitcnt lgkmcnt(0)
	v_cvt_pk_bf16_f32 v6, v14, v15
	v_cvt_pk_bf16_f32 v7, v16, v17
	ds_read_b128 v[150:153], v213
	ds_read_b128 v[26:29], v213 offset:64
	ds_read_b128 v[14:17], v213 offset:128
	ds_read_b128 v[2:5], v213 offset:192
	s_waitcnt lgkmcnt(0)
	v_cvt_pk_bf16_f32 v137, v8, v9
	v_cvt_pk_bf16_f32 v8, v10, v11
	v_cvt_pk_bf16_f32 v9, v12, v13
	s_add_i32 s37, s37, 16
	s_cmp_lg_u32 s40, 48
	s_cselect_b32 s10, s37, 48
	v_or_b32_e32 v20, s10, v184
	v_add_u32_e32 v21, s33, v20
	v_cmp_lt_i32_e32 vcc, 1, v21
	v_cmp_gt_i32_e64 s[10:11], s48, v21
	v_add_u32_e32 v0, -2, v20
	s_and_b64 vcc, vcc, s[10:11]
	v_cndmask_b32_e32 v10, v20, v0, vcc
	v_cmp_lt_i32_e32 vcc, 0, v21
	v_cmp_ge_i32_e64 s[10:11], s3, v21
	s_and_b64 vcc, vcc, s[10:11]
	v_subbrev_co_u32_e32 v12, vcc, 0, v20, vcc
	v_cmp_lt_i32_e32 vcc, -2, v21
	v_cmp_gt_i32_e64 s[10:11], s49, v21
	v_ashrrev_i32_e32 v11, 31, v10
	v_lshlrev_b32_e32 v0, 10, v20
	s_and_b64 vcc, vcc, s[10:11]
	v_lshlrev_b64 v[10:11], 10, v[10:11]
	v_ashrrev_i32_e32 v13, 31, v12
	v_lshl_add_u64 v[18:19], v[140:141], 0, v[0:1]
	v_addc_co_u32_e32 v0, vcc, 0, v20, vcc
	v_lshl_add_u64 v[10:11], v[140:141], 0, v[10:11]
	v_lshlrev_b64 v[12:13], 10, v[12:13]
	v_lshlrev_b32_e32 v0, 10, v0
	v_lshl_add_u64 v[12:13], v[140:141], 0, v[12:13]
	v_lshl_add_u64 v[20:21], v[140:141], 0, v[0:1]
	global_load_dwordx4 v[126:129], v[10:11], off
	global_load_dwordx4 v[110:113], v[10:11], off offset:64
	global_load_dwordx4 v[122:125], v[12:13], off
	global_load_dwordx4 v[106:109], v[12:13], off offset:64
	global_load_dwordx4 v[118:121], v[18:19], off
	global_load_dwordx4 v[102:105], v[18:19], off offset:64
	global_load_dwordx4 v[114:117], v[20:21], off
	global_load_dwordx4 v[98:101], v[20:21], off offset:64
	ds_read_b128 v[158:161], v197
	ds_read_b128 v[162:165], v198
	ds_read_b128 v[166:169], v199
	v_mfma_f32_16x16x32_bf16 v[10:13], v[34:37], v[134:137], 0
	s_mov_b64 s[10:11], -1
	v_mfma_f32_16x16x32_bf16 v[18:21], v[42:45], v[134:137], 0
	v_mfma_f32_16x16x32_bf16 v[146:149], v[38:41], v[6:9], v[10:13]
	v_mfma_f32_16x16x32_bf16 v[10:13], v[50:53], v[134:137], 0
	v_mfma_f32_16x16x32_bf16 v[154:157], v[46:49], v[6:9], v[18:21]
	v_mfma_f32_16x16x32_bf16 v[18:21], v[58:61], v[134:137], 0
	v_mfma_f32_16x16x32_bf16 v[130:133], v[54:57], v[6:9], v[10:13]
	v_mfma_f32_16x16x32_bf16 v[10:13], v[66:69], v[134:137], 0
	v_mfma_f32_16x16x32_bf16 v[30:33], v[62:65], v[6:9], v[18:21]
	v_mfma_f32_16x16x32_bf16 v[18:21], v[70:73], v[134:137], 0
	v_mfma_f32_16x16x32_bf16 v[22:25], v[74:77], v[6:9], v[10:13]
	v_mfma_f32_16x16x32_bf16 v[10:13], v[82:85], v[134:137], 0
	v_mfma_f32_16x16x32_bf16 v[134:137], v[86:89], v[134:137], 0
	v_mfma_f32_16x16x32_bf16 v[18:21], v[78:81], v[6:9], v[18:21]
	v_mfma_f32_16x16x32_bf16 v[10:13], v[90:93], v[6:9], v[10:13]
	v_mfma_f32_16x16x32_bf16 v[6:9], v[94:97], v[6:9], v[134:137]
	s_nop 4
	ds_read_b128 v[246:249], v202
	ds_read_b128 v[250:253], v203
	ds_read_b128 v[134:137], v204
	v_mov_b32_e32 v170, 0xbfb8aa3b
	v_mov_b32_e32 v226, 0x3fb17218
	s_waitcnt lgkmcnt(3)
	v_pk_fma_f32 v[146:147], v[146:147], v[170:171], v[158:159] op_sel_hi:[1,0,1]
	v_pk_fma_f32 v[148:149], v[148:149], v[170:171], v[160:161] op_sel_hi:[1,0,1]
	v_pk_fma_f32 v[154:155], v[154:155], v[170:171], v[162:163] op_sel_hi:[1,0,1]
	v_pk_fma_f32 v[156:157], v[156:157], v[170:171], v[164:165] op_sel_hi:[1,0,1]
	v_exp_f32_e32 v146, v146
	v_exp_f32_e32 v147, v147
	v_exp_f32_e32 v148, v148
	v_exp_f32_e32 v149, v149
	v_exp_f32_e32 v154, v154
	v_exp_f32_e32 v155, v155
	v_exp_f32_e32 v156, v156
	v_exp_f32_e32 v157, v157
	v_pk_add_f32 v[146:147], v[146:147], 1.0 op_sel_hi:[1,0]
	v_pk_add_f32 v[148:149], v[148:149], 1.0 op_sel_hi:[1,0]
	v_pk_add_f32 v[154:155], v[154:155], 1.0 op_sel_hi:[1,0]
	v_pk_add_f32 v[156:157], v[156:157], 1.0 op_sel_hi:[1,0]
	v_rcp_f32_e32 v146, v146
	v_rcp_f32_e32 v147, v147
	v_rcp_f32_e32 v148, v148
	v_rcp_f32_e32 v149, v149
	v_rcp_f32_e32 v154, v154
	v_rcp_f32_e32 v155, v155
	v_rcp_f32_e32 v156, v156
	v_rcp_f32_e32 v157, v157
	v_pk_mul_f32 v[166:167], v[166:167], v[146:147]
	v_pk_mul_f32 v[168:169], v[168:169], v[148:149]
	v_exp_f32_e32 v146, v166
	v_exp_f32_e32 v147, v167
	v_exp_f32_e32 v148, v168
	v_exp_f32_e32 v149, v169
	v_pk_mul_f32 v[158:159], v[166:167], v[226:227] op_sel_hi:[1,0]
	v_pk_mul_f32 v[160:161], v[168:169], v[226:227] op_sel_hi:[1,0]
	v_pk_fma_f32 v[162:163], v[158:159], 0.5, 1.0 op_sel_hi:[1,0,0]
	v_pk_fma_f32 v[164:165], v[160:161], 0.5, 1.0 op_sel_hi:[1,0,0]
	v_pk_mul_f32 v[162:163], v[162:163], v[158:159] neg_lo:[0,1] neg_hi:[0,1]
	v_pk_mul_f32 v[164:165], v[164:165], v[160:161] neg_lo:[0,1] neg_hi:[0,1]
	v_cmp_lt_f32_e32 vcc, s72, v158
	v_cmp_lt_f32_e64 s[12:13], s72, v159
	v_cmp_lt_f32_e64 s[14:15], s72, v160
	v_cmp_lt_f32_e64 s[16:17], s72, v161
	v_pk_fma_f32 v[158:159], v[146:147], v[146:147], 1.0 op_sel_hi:[1,1,0] neg_lo:[1,0,0] neg_hi:[1,0,0]
	v_pk_fma_f32 v[160:161], v[148:149], v[148:149], 1.0 op_sel_hi:[1,1,0] neg_lo:[1,0,0] neg_hi:[1,0,0]
	v_cndmask_b32_e32 v158, v158, v162, vcc
	v_cndmask_b32_e64 v159, v159, v163, s[12:13]
	v_cndmask_b32_e64 v160, v160, v164, s[14:15]
	v_cndmask_b32_e64 v161, v161, v165, s[16:17]
	v_sqrt_f32_e32 v158, v158
	v_sqrt_f32_e32 v159, v159
	v_sqrt_f32_e32 v160, v160
	v_sqrt_f32_e32 v161, v161
	v_pk_mul_f32 v[154:155], v[154:155], v[158:159]
	v_pk_mul_f32 v[156:157], v[156:157], v[160:161]
	v_pk_mul_f32 v[150:151], v[150:151], v[154:155]
	v_pk_mul_f32 v[152:153], v[152:153], v[156:157]
	v_cvt_pkrtz_f16_f32 v162, v166, v150
	v_cvt_pkrtz_f16_f32 v163, v167, v151
	v_cvt_pkrtz_f16_f32 v164, v168, v152
	v_cvt_pkrtz_f16_f32 v165, v169, v153
	global_store_dwordx4 v[142:143], v[162:165], off offset:-2048
	ds_read_b128 v[158:161], v205
	ds_read_b128 v[162:165], v206
	ds_read_b128 v[166:169], v207
	s_waitcnt lgkmcnt(3)
	v_pk_fma_f32 v[130:131], v[130:131], v[170:171], v[246:247] op_sel_hi:[1,0,1]
	v_pk_fma_f32 v[132:133], v[132:133], v[170:171], v[248:249] op_sel_hi:[1,0,1]
	v_pk_fma_f32 v[30:31], v[30:31], v[170:171], v[250:251] op_sel_hi:[1,0,1]
	v_pk_fma_f32 v[32:33], v[32:33], v[170:171], v[252:253] op_sel_hi:[1,0,1]
	v_exp_f32_e32 v130, v130
	v_exp_f32_e32 v131, v131
	v_exp_f32_e32 v132, v132
	v_exp_f32_e32 v133, v133
	v_exp_f32_e32 v30, v30
	v_exp_f32_e32 v31, v31
	v_exp_f32_e32 v32, v32
	v_exp_f32_e32 v33, v33
	v_pk_add_f32 v[130:131], v[130:131], 1.0 op_sel_hi:[1,0]
	v_pk_add_f32 v[132:133], v[132:133], 1.0 op_sel_hi:[1,0]
	v_pk_add_f32 v[30:31], v[30:31], 1.0 op_sel_hi:[1,0]
	v_pk_add_f32 v[32:33], v[32:33], 1.0 op_sel_hi:[1,0]
	v_rcp_f32_e32 v130, v130
	v_rcp_f32_e32 v131, v131
	v_rcp_f32_e32 v132, v132
	v_rcp_f32_e32 v133, v133
	v_rcp_f32_e32 v30, v30
	v_rcp_f32_e32 v31, v31
	v_rcp_f32_e32 v32, v32
	v_rcp_f32_e32 v33, v33
	v_pk_mul_f32 v[134:135], v[134:135], v[130:131]
	v_pk_mul_f32 v[136:137], v[136:137], v[132:133]
	v_exp_f32_e32 v130, v134
	v_exp_f32_e32 v131, v135
	v_exp_f32_e32 v132, v136
	v_exp_f32_e32 v133, v137
	v_pk_mul_f32 v[246:247], v[134:135], v[226:227] op_sel_hi:[1,0]
	v_pk_mul_f32 v[248:249], v[136:137], v[226:227] op_sel_hi:[1,0]
	v_pk_fma_f32 v[250:251], v[246:247], 0.5, 1.0 op_sel_hi:[1,0,0]
	v_pk_fma_f32 v[252:253], v[248:249], 0.5, 1.0 op_sel_hi:[1,0,0]
	v_pk_mul_f32 v[250:251], v[250:251], v[246:247] neg_lo:[0,1] neg_hi:[0,1]
	v_pk_mul_f32 v[252:253], v[252:253], v[248:249] neg_lo:[0,1] neg_hi:[0,1]
	v_cmp_lt_f32_e32 vcc, s72, v246
	v_cmp_lt_f32_e64 s[12:13], s72, v247
	v_cmp_lt_f32_e64 s[14:15], s72, v248
	v_cmp_lt_f32_e64 s[16:17], s72, v249
	v_pk_fma_f32 v[246:247], v[130:131], v[130:131], 1.0 op_sel_hi:[1,1,0] neg_lo:[1,0,0] neg_hi:[1,0,0]
	v_pk_fma_f32 v[248:249], v[132:133], v[132:133], 1.0 op_sel_hi:[1,1,0] neg_lo:[1,0,0] neg_hi:[1,0,0]
	v_cndmask_b32_e32 v246, v246, v250, vcc
	v_cndmask_b32_e64 v247, v247, v251, s[12:13]
	v_cndmask_b32_e64 v248, v248, v252, s[14:15]
	v_cndmask_b32_e64 v249, v249, v253, s[16:17]
	v_sqrt_f32_e32 v246, v246
	v_sqrt_f32_e32 v247, v247
	v_sqrt_f32_e32 v248, v248
	v_sqrt_f32_e32 v249, v249
	v_pk_mul_f32 v[30:31], v[30:31], v[246:247]
	v_pk_mul_f32 v[32:33], v[32:33], v[248:249]
	v_pk_mul_f32 v[26:27], v[26:27], v[30:31]
	v_pk_mul_f32 v[28:29], v[28:29], v[32:33]
	v_cvt_pkrtz_f16_f32 v250, v134, v26
	v_cvt_pkrtz_f16_f32 v251, v135, v27
	v_cvt_pkrtz_f16_f32 v252, v136, v28
	v_cvt_pkrtz_f16_f32 v253, v137, v29
	global_store_dwordx4 v[142:143], v[250:253], off offset:-1024
	ds_read_b128 v[246:249], v208
	ds_read_b128 v[250:253], v209
	ds_read_b128 v[134:137], v210
	s_waitcnt lgkmcnt(3)
	v_pk_fma_f32 v[22:23], v[22:23], v[170:171], v[158:159] op_sel_hi:[1,0,1]
	v_pk_fma_f32 v[24:25], v[24:25], v[170:171], v[160:161] op_sel_hi:[1,0,1]
	v_pk_fma_f32 v[18:19], v[18:19], v[170:171], v[162:163] op_sel_hi:[1,0,1]
	v_pk_fma_f32 v[20:21], v[20:21], v[170:171], v[164:165] op_sel_hi:[1,0,1]
	v_exp_f32_e32 v22, v22
	v_exp_f32_e32 v23, v23
	v_exp_f32_e32 v24, v24
	v_exp_f32_e32 v25, v25
	v_exp_f32_e32 v18, v18
	v_exp_f32_e32 v19, v19
	v_exp_f32_e32 v20, v20
	v_exp_f32_e32 v21, v21
	v_pk_add_f32 v[22:23], v[22:23], 1.0 op_sel_hi:[1,0]
	v_pk_add_f32 v[24:25], v[24:25], 1.0 op_sel_hi:[1,0]
	v_pk_add_f32 v[18:19], v[18:19], 1.0 op_sel_hi:[1,0]
	v_pk_add_f32 v[20:21], v[20:21], 1.0 op_sel_hi:[1,0]
	v_rcp_f32_e32 v22, v22
	v_rcp_f32_e32 v23, v23
	v_rcp_f32_e32 v24, v24
	v_rcp_f32_e32 v25, v25
	v_rcp_f32_e32 v18, v18
	v_rcp_f32_e32 v19, v19
	v_rcp_f32_e32 v20, v20
	v_rcp_f32_e32 v21, v21
	v_pk_mul_f32 v[166:167], v[166:167], v[22:23]
	v_pk_mul_f32 v[168:169], v[168:169], v[24:25]
	v_exp_f32_e32 v22, v166
	v_exp_f32_e32 v23, v167
	v_exp_f32_e32 v24, v168
	v_exp_f32_e32 v25, v169
	v_pk_mul_f32 v[158:159], v[166:167], v[226:227] op_sel_hi:[1,0]
	v_pk_mul_f32 v[160:161], v[168:169], v[226:227] op_sel_hi:[1,0]
	v_pk_fma_f32 v[162:163], v[158:159], 0.5, 1.0 op_sel_hi:[1,0,0]
	v_pk_fma_f32 v[164:165], v[160:161], 0.5, 1.0 op_sel_hi:[1,0,0]
	v_pk_mul_f32 v[162:163], v[162:163], v[158:159] neg_lo:[0,1] neg_hi:[0,1]
	v_pk_mul_f32 v[164:165], v[164:165], v[160:161] neg_lo:[0,1] neg_hi:[0,1]
	v_cmp_lt_f32_e32 vcc, s72, v158
	v_cmp_lt_f32_e64 s[12:13], s72, v159
	v_cmp_lt_f32_e64 s[14:15], s72, v160
	v_cmp_lt_f32_e64 s[16:17], s72, v161
	v_pk_fma_f32 v[158:159], v[22:23], v[22:23], 1.0 op_sel_hi:[1,1,0] neg_lo:[1,0,0] neg_hi:[1,0,0]
	v_pk_fma_f32 v[160:161], v[24:25], v[24:25], 1.0 op_sel_hi:[1,1,0] neg_lo:[1,0,0] neg_hi:[1,0,0]
	v_cndmask_b32_e32 v158, v158, v162, vcc
	v_cndmask_b32_e64 v159, v159, v163, s[12:13]
	v_cndmask_b32_e64 v160, v160, v164, s[14:15]
	v_cndmask_b32_e64 v161, v161, v165, s[16:17]
	v_sqrt_f32_e32 v158, v158
	v_sqrt_f32_e32 v159, v159
	v_sqrt_f32_e32 v160, v160
	v_sqrt_f32_e32 v161, v161
	v_pk_mul_f32 v[18:19], v[18:19], v[158:159]
	v_pk_mul_f32 v[20:21], v[20:21], v[160:161]
	v_pk_mul_f32 v[14:15], v[14:15], v[18:19]
	v_pk_mul_f32 v[16:17], v[16:17], v[20:21]
	v_cvt_pkrtz_f16_f32 v162, v166, v14
	v_cvt_pkrtz_f16_f32 v163, v167, v15
	v_cvt_pkrtz_f16_f32 v164, v168, v16
	v_cvt_pkrtz_f16_f32 v165, v169, v17
	global_store_dwordx4 v[142:143], v[162:165], off
	s_waitcnt lgkmcnt(0)
	v_pk_fma_f32 v[10:11], v[10:11], v[170:171], v[246:247] op_sel_hi:[1,0,1]
	v_pk_fma_f32 v[12:13], v[12:13], v[170:171], v[248:249] op_sel_hi:[1,0,1]
	v_pk_fma_f32 v[6:7], v[6:7], v[170:171], v[250:251] op_sel_hi:[1,0,1]
	v_pk_fma_f32 v[8:9], v[8:9], v[170:171], v[252:253] op_sel_hi:[1,0,1]
	v_exp_f32_e32 v10, v10
	v_exp_f32_e32 v11, v11
	v_exp_f32_e32 v12, v12
	v_exp_f32_e32 v13, v13
	v_exp_f32_e32 v6, v6
	v_exp_f32_e32 v7, v7
	v_exp_f32_e32 v8, v8
	v_exp_f32_e32 v9, v9
	v_pk_add_f32 v[10:11], v[10:11], 1.0 op_sel_hi:[1,0]
	v_pk_add_f32 v[12:13], v[12:13], 1.0 op_sel_hi:[1,0]
	v_pk_add_f32 v[6:7], v[6:7], 1.0 op_sel_hi:[1,0]
	v_pk_add_f32 v[8:9], v[8:9], 1.0 op_sel_hi:[1,0]
	v_rcp_f32_e32 v10, v10
	v_rcp_f32_e32 v11, v11
	v_rcp_f32_e32 v12, v12
	v_rcp_f32_e32 v13, v13
	v_rcp_f32_e32 v6, v6
	v_rcp_f32_e32 v7, v7
	v_rcp_f32_e32 v8, v8
	v_rcp_f32_e32 v9, v9
	v_pk_mul_f32 v[134:135], v[134:135], v[10:11]
	v_pk_mul_f32 v[136:137], v[136:137], v[12:13]
	v_exp_f32_e32 v10, v134
	v_exp_f32_e32 v11, v135
	v_exp_f32_e32 v12, v136
	v_exp_f32_e32 v13, v137
	v_pk_mul_f32 v[246:247], v[134:135], v[226:227] op_sel_hi:[1,0]
	v_pk_mul_f32 v[248:249], v[136:137], v[226:227] op_sel_hi:[1,0]
	v_pk_fma_f32 v[250:251], v[246:247], 0.5, 1.0 op_sel_hi:[1,0,0]
	v_pk_fma_f32 v[252:253], v[248:249], 0.5, 1.0 op_sel_hi:[1,0,0]
	v_pk_mul_f32 v[250:251], v[250:251], v[246:247] neg_lo:[0,1] neg_hi:[0,1]
	v_pk_mul_f32 v[252:253], v[252:253], v[248:249] neg_lo:[0,1] neg_hi:[0,1]
	v_cmp_lt_f32_e32 vcc, s72, v246
	v_cmp_lt_f32_e64 s[12:13], s72, v247
	v_cmp_lt_f32_e64 s[14:15], s72, v248
	v_cmp_lt_f32_e64 s[16:17], s72, v249
	v_pk_fma_f32 v[246:247], v[10:11], v[10:11], 1.0 op_sel_hi:[1,1,0] neg_lo:[1,0,0] neg_hi:[1,0,0]
	v_pk_fma_f32 v[248:249], v[12:13], v[12:13], 1.0 op_sel_hi:[1,1,0] neg_lo:[1,0,0] neg_hi:[1,0,0]
	v_cndmask_b32_e32 v246, v246, v250, vcc
	v_cndmask_b32_e64 v247, v247, v251, s[12:13]
	v_cndmask_b32_e64 v248, v248, v252, s[14:15]
	v_cndmask_b32_e64 v249, v249, v253, s[16:17]
	v_sqrt_f32_e32 v246, v246
	v_sqrt_f32_e32 v247, v247
	v_sqrt_f32_e32 v248, v248
	v_sqrt_f32_e32 v249, v249
	v_pk_mul_f32 v[6:7], v[6:7], v[246:247]
	v_pk_mul_f32 v[8:9], v[8:9], v[248:249]
	v_pk_mul_f32 v[2:3], v[2:3], v[6:7]
	v_pk_mul_f32 v[4:5], v[4:5], v[8:9]
	v_cvt_pkrtz_f16_f32 v250, v134, v2
	v_cvt_pkrtz_f16_f32 v251, v135, v3
	v_cvt_pkrtz_f16_f32 v252, v136, v4
	v_cvt_pkrtz_f16_f32 v253, v137, v5
	global_store_dwordx4 v[142:143], v[250:253], off offset:1024
	s_and_b64 vcc, exec, s[44:45]
	s_cbranch_vccz .LBB0_341
	s_mov_b32 s10, 0x10001
	s_mov_b32 s11, 0x10001
	s_mov_b64 s[12:13], exec
	s_mov_b64 exec, s[10:11]
	v_fma_f32 v150, v172, v150, v214
	v_mul_f32_e32 v146, v146, v172
	v_fma_f32 v151, v173, v151, v215
	v_mul_f32_e32 v147, v147, v173
	v_fma_f32 v152, v174, v152, v216
	v_mul_f32_e32 v148, v148, v174
	v_fma_f32 v153, v175, v153, v217
	v_mul_f32_e32 v149, v149, v175
	v_fma_f32 v26, v176, v26, v218
	v_mul_f32_e32 v130, v130, v176
	v_fma_f32 v27, v177, v27, v219
	v_mul_f32_e32 v131, v131, v177
	v_fma_f32 v28, v178, v28, v220
	v_mul_f32_e32 v132, v132, v178
	v_fma_f32 v29, v179, v29, v221
	v_mul_f32_e32 v133, v133, v179
	v_fma_f32 v14, v180, v14, v222
	v_mul_f32_e32 v22, v22, v180
	v_fma_f32 v15, v181, v15, v223
	v_mul_f32_e32 v23, v23, v181
	v_fma_f32 v16, v182, v16, v224
	v_mul_f32_e32 v24, v24, v182
	v_fma_f32 v17, v183, v17, v225
	v_mul_f32_e32 v25, v25, v183
	v_fma_f32 v2, v192, v2, v234
	v_mul_f32_e32 v10, v10, v192
	v_fma_f32 v3, v193, v3, v235
	v_mul_f32_e32 v11, v11, v193
	v_fma_f32 v4, v194, v4, v236
	v_mul_f32_e32 v12, v12, v194
	v_fma_f32 v5, v195, v5, v237
	v_mul_f32_e32 v13, v13, v195
	s_mov_b64 exec, s[12:13]
	s_nop 4
	v_fmac_f32_dpp v150, v150, v146 row_shl:1 row_mask:0xf bank_mask:0xf bound_ctrl:1
	v_mul_f32_dpp v146, v146, v146 row_shl:1 row_mask:0xf bank_mask:0xf
	v_fmac_f32_dpp v151, v151, v147 row_shl:1 row_mask:0xf bank_mask:0xf bound_ctrl:1
	v_mul_f32_dpp v147, v147, v147 row_shl:1 row_mask:0xf bank_mask:0xf
	v_fmac_f32_dpp v152, v152, v148 row_shl:1 row_mask:0xf bank_mask:0xf bound_ctrl:1
	v_mul_f32_dpp v148, v148, v148 row_shl:1 row_mask:0xf bank_mask:0xf
	v_fmac_f32_dpp v153, v153, v149 row_shl:1 row_mask:0xf bank_mask:0xf bound_ctrl:1
	v_mul_f32_dpp v149, v149, v149 row_shl:1 row_mask:0xf bank_mask:0xf
	v_fmac_f32_dpp v26, v26, v130 row_shl:1 row_mask:0xf bank_mask:0xf bound_ctrl:1
	v_mul_f32_dpp v130, v130, v130 row_shl:1 row_mask:0xf bank_mask:0xf
	v_fmac_f32_dpp v27, v27, v131 row_shl:1 row_mask:0xf bank_mask:0xf bound_ctrl:1
	v_mul_f32_dpp v131, v131, v131 row_shl:1 row_mask:0xf bank_mask:0xf
	v_fmac_f32_dpp v28, v28, v132 row_shl:1 row_mask:0xf bank_mask:0xf bound_ctrl:1
	v_mul_f32_dpp v132, v132, v132 row_shl:1 row_mask:0xf bank_mask:0xf
	v_fmac_f32_dpp v29, v29, v133 row_shl:1 row_mask:0xf bank_mask:0xf bound_ctrl:1
	v_mul_f32_dpp v133, v133, v133 row_shl:1 row_mask:0xf bank_mask:0xf
	v_fmac_f32_dpp v14, v14, v22 row_shl:1 row_mask:0xf bank_mask:0xf bound_ctrl:1
	v_mul_f32_dpp v22, v22, v22 row_shl:1 row_mask:0xf bank_mask:0xf
	v_fmac_f32_dpp v15, v15, v23 row_shl:1 row_mask:0xf bank_mask:0xf bound_ctrl:1
	v_mul_f32_dpp v23, v23, v23 row_shl:1 row_mask:0xf bank_mask:0xf
	v_fmac_f32_dpp v16, v16, v24 row_shl:1 row_mask:0xf bank_mask:0xf bound_ctrl:1
	v_mul_f32_dpp v24, v24, v24 row_shl:1 row_mask:0xf bank_mask:0xf
	v_fmac_f32_dpp v17, v17, v25 row_shl:1 row_mask:0xf bank_mask:0xf bound_ctrl:1
	v_mul_f32_dpp v25, v25, v25 row_shl:1 row_mask:0xf bank_mask:0xf
	v_fmac_f32_dpp v2, v2, v10 row_shl:1 row_mask:0xf bank_mask:0xf bound_ctrl:1
	v_mul_f32_dpp v10, v10, v10 row_shl:1 row_mask:0xf bank_mask:0xf
	v_fmac_f32_dpp v3, v3, v11 row_shl:1 row_mask:0xf bank_mask:0xf bound_ctrl:1
	v_mul_f32_dpp v11, v11, v11 row_shl:1 row_mask:0xf bank_mask:0xf
	v_fmac_f32_dpp v4, v4, v12 row_shl:1 row_mask:0xf bank_mask:0xf bound_ctrl:1
	v_mul_f32_dpp v12, v12, v12 row_shl:1 row_mask:0xf bank_mask:0xf
	v_fmac_f32_dpp v5, v5, v13 row_shl:1 row_mask:0xf bank_mask:0xf bound_ctrl:1
	v_mul_f32_dpp v13, v13, v13 row_shl:1 row_mask:0xf bank_mask:0xf
	v_fmac_f32_dpp v150, v150, v146 row_shl:2 row_mask:0xf bank_mask:0xf bound_ctrl:1
	v_mul_f32_dpp v146, v146, v146 row_shl:2 row_mask:0xf bank_mask:0xf
	v_fmac_f32_dpp v151, v151, v147 row_shl:2 row_mask:0xf bank_mask:0xf bound_ctrl:1
	v_mul_f32_dpp v147, v147, v147 row_shl:2 row_mask:0xf bank_mask:0xf
	v_fmac_f32_dpp v152, v152, v148 row_shl:2 row_mask:0xf bank_mask:0xf bound_ctrl:1
	v_mul_f32_dpp v148, v148, v148 row_shl:2 row_mask:0xf bank_mask:0xf
	v_fmac_f32_dpp v153, v153, v149 row_shl:2 row_mask:0xf bank_mask:0xf bound_ctrl:1
	v_mul_f32_dpp v149, v149, v149 row_shl:2 row_mask:0xf bank_mask:0xf
	v_fmac_f32_dpp v26, v26, v130 row_shl:2 row_mask:0xf bank_mask:0xf bound_ctrl:1
	v_mul_f32_dpp v130, v130, v130 row_shl:2 row_mask:0xf bank_mask:0xf
	v_fmac_f32_dpp v27, v27, v131 row_shl:2 row_mask:0xf bank_mask:0xf bound_ctrl:1
	v_mul_f32_dpp v131, v131, v131 row_shl:2 row_mask:0xf bank_mask:0xf
	v_fmac_f32_dpp v28, v28, v132 row_shl:2 row_mask:0xf bank_mask:0xf bound_ctrl:1
	v_mul_f32_dpp v132, v132, v132 row_shl:2 row_mask:0xf bank_mask:0xf
	v_fmac_f32_dpp v29, v29, v133 row_shl:2 row_mask:0xf bank_mask:0xf bound_ctrl:1
	v_mul_f32_dpp v133, v133, v133 row_shl:2 row_mask:0xf bank_mask:0xf
	v_fmac_f32_dpp v14, v14, v22 row_shl:2 row_mask:0xf bank_mask:0xf bound_ctrl:1
	v_mul_f32_dpp v22, v22, v22 row_shl:2 row_mask:0xf bank_mask:0xf
	v_fmac_f32_dpp v15, v15, v23 row_shl:2 row_mask:0xf bank_mask:0xf bound_ctrl:1
	v_mul_f32_dpp v23, v23, v23 row_shl:2 row_mask:0xf bank_mask:0xf
	v_fmac_f32_dpp v16, v16, v24 row_shl:2 row_mask:0xf bank_mask:0xf bound_ctrl:1
	v_mul_f32_dpp v24, v24, v24 row_shl:2 row_mask:0xf bank_mask:0xf
	v_fmac_f32_dpp v17, v17, v25 row_shl:2 row_mask:0xf bank_mask:0xf bound_ctrl:1
	v_mul_f32_dpp v25, v25, v25 row_shl:2 row_mask:0xf bank_mask:0xf
	v_fmac_f32_dpp v2, v2, v10 row_shl:2 row_mask:0xf bank_mask:0xf bound_ctrl:1
	v_mul_f32_dpp v10, v10, v10 row_shl:2 row_mask:0xf bank_mask:0xf
	v_fmac_f32_dpp v3, v3, v11 row_shl:2 row_mask:0xf bank_mask:0xf bound_ctrl:1
	v_mul_f32_dpp v11, v11, v11 row_shl:2 row_mask:0xf bank_mask:0xf
	v_fmac_f32_dpp v4, v4, v12 row_shl:2 row_mask:0xf bank_mask:0xf bound_ctrl:1
	v_mul_f32_dpp v12, v12, v12 row_shl:2 row_mask:0xf bank_mask:0xf
	v_fmac_f32_dpp v5, v5, v13 row_shl:2 row_mask:0xf bank_mask:0xf bound_ctrl:1
	v_mul_f32_dpp v13, v13, v13 row_shl:2 row_mask:0xf bank_mask:0xf
	v_fmac_f32_dpp v150, v150, v146 row_shl:4 row_mask:0xf bank_mask:0xf bound_ctrl:1
	v_mul_f32_dpp v146, v146, v146 row_shl:4 row_mask:0xf bank_mask:0xf
	v_fmac_f32_dpp v151, v151, v147 row_shl:4 row_mask:0xf bank_mask:0xf bound_ctrl:1
	v_mul_f32_dpp v147, v147, v147 row_shl:4 row_mask:0xf bank_mask:0xf
	v_fmac_f32_dpp v152, v152, v148 row_shl:4 row_mask:0xf bank_mask:0xf bound_ctrl:1
	v_mul_f32_dpp v148, v148, v148 row_shl:4 row_mask:0xf bank_mask:0xf
	v_fmac_f32_dpp v153, v153, v149 row_shl:4 row_mask:0xf bank_mask:0xf bound_ctrl:1
	v_mul_f32_dpp v149, v149, v149 row_shl:4 row_mask:0xf bank_mask:0xf
	v_fmac_f32_dpp v26, v26, v130 row_shl:4 row_mask:0xf bank_mask:0xf bound_ctrl:1
	v_mul_f32_dpp v130, v130, v130 row_shl:4 row_mask:0xf bank_mask:0xf
	v_fmac_f32_dpp v27, v27, v131 row_shl:4 row_mask:0xf bank_mask:0xf bound_ctrl:1
	v_mul_f32_dpp v131, v131, v131 row_shl:4 row_mask:0xf bank_mask:0xf
	v_fmac_f32_dpp v28, v28, v132 row_shl:4 row_mask:0xf bank_mask:0xf bound_ctrl:1
	v_mul_f32_dpp v132, v132, v132 row_shl:4 row_mask:0xf bank_mask:0xf
	v_fmac_f32_dpp v29, v29, v133 row_shl:4 row_mask:0xf bank_mask:0xf bound_ctrl:1
	v_mul_f32_dpp v133, v133, v133 row_shl:4 row_mask:0xf bank_mask:0xf
	v_fmac_f32_dpp v14, v14, v22 row_shl:4 row_mask:0xf bank_mask:0xf bound_ctrl:1
	v_mul_f32_dpp v22, v22, v22 row_shl:4 row_mask:0xf bank_mask:0xf
	v_fmac_f32_dpp v15, v15, v23 row_shl:4 row_mask:0xf bank_mask:0xf bound_ctrl:1
	v_mul_f32_dpp v23, v23, v23 row_shl:4 row_mask:0xf bank_mask:0xf
	v_fmac_f32_dpp v16, v16, v24 row_shl:4 row_mask:0xf bank_mask:0xf bound_ctrl:1
	v_mul_f32_dpp v24, v24, v24 row_shl:4 row_mask:0xf bank_mask:0xf
	v_fmac_f32_dpp v17, v17, v25 row_shl:4 row_mask:0xf bank_mask:0xf bound_ctrl:1
	v_mul_f32_dpp v25, v25, v25 row_shl:4 row_mask:0xf bank_mask:0xf
	v_fmac_f32_dpp v2, v2, v10 row_shl:4 row_mask:0xf bank_mask:0xf bound_ctrl:1
	v_mul_f32_dpp v10, v10, v10 row_shl:4 row_mask:0xf bank_mask:0xf
	v_fmac_f32_dpp v3, v3, v11 row_shl:4 row_mask:0xf bank_mask:0xf bound_ctrl:1
	v_mul_f32_dpp v11, v11, v11 row_shl:4 row_mask:0xf bank_mask:0xf
	v_fmac_f32_dpp v4, v4, v12 row_shl:4 row_mask:0xf bank_mask:0xf bound_ctrl:1
	v_mul_f32_dpp v12, v12, v12 row_shl:4 row_mask:0xf bank_mask:0xf
	v_fmac_f32_dpp v5, v5, v13 row_shl:4 row_mask:0xf bank_mask:0xf bound_ctrl:1
	v_mul_f32_dpp v13, v13, v13 row_shl:4 row_mask:0xf bank_mask:0xf
	v_fmac_f32_dpp v150, v150, v146 row_shl:8 row_mask:0xf bank_mask:0xf bound_ctrl:1
	v_mul_f32_dpp v146, v146, v146 row_shl:8 row_mask:0xf bank_mask:0xf
	v_fmac_f32_dpp v151, v151, v147 row_shl:8 row_mask:0xf bank_mask:0xf bound_ctrl:1
	v_mul_f32_dpp v147, v147, v147 row_shl:8 row_mask:0xf bank_mask:0xf
	v_fmac_f32_dpp v152, v152, v148 row_shl:8 row_mask:0xf bank_mask:0xf bound_ctrl:1
	v_mul_f32_dpp v148, v148, v148 row_shl:8 row_mask:0xf bank_mask:0xf
	v_fmac_f32_dpp v153, v153, v149 row_shl:8 row_mask:0xf bank_mask:0xf bound_ctrl:1
	v_mul_f32_dpp v149, v149, v149 row_shl:8 row_mask:0xf bank_mask:0xf
	v_fmac_f32_dpp v26, v26, v130 row_shl:8 row_mask:0xf bank_mask:0xf bound_ctrl:1
	v_mul_f32_dpp v130, v130, v130 row_shl:8 row_mask:0xf bank_mask:0xf
	v_fmac_f32_dpp v27, v27, v131 row_shl:8 row_mask:0xf bank_mask:0xf bound_ctrl:1
	v_mul_f32_dpp v131, v131, v131 row_shl:8 row_mask:0xf bank_mask:0xf
	v_fmac_f32_dpp v28, v28, v132 row_shl:8 row_mask:0xf bank_mask:0xf bound_ctrl:1
	v_mul_f32_dpp v132, v132, v132 row_shl:8 row_mask:0xf bank_mask:0xf
	v_fmac_f32_dpp v29, v29, v133 row_shl:8 row_mask:0xf bank_mask:0xf bound_ctrl:1
	v_mul_f32_dpp v133, v133, v133 row_shl:8 row_mask:0xf bank_mask:0xf
	v_fmac_f32_dpp v14, v14, v22 row_shl:8 row_mask:0xf bank_mask:0xf bound_ctrl:1
	v_mul_f32_dpp v22, v22, v22 row_shl:8 row_mask:0xf bank_mask:0xf
	v_fmac_f32_dpp v15, v15, v23 row_shl:8 row_mask:0xf bank_mask:0xf bound_ctrl:1
	v_mul_f32_dpp v23, v23, v23 row_shl:8 row_mask:0xf bank_mask:0xf
	v_fmac_f32_dpp v16, v16, v24 row_shl:8 row_mask:0xf bank_mask:0xf bound_ctrl:1
	v_mul_f32_dpp v24, v24, v24 row_shl:8 row_mask:0xf bank_mask:0xf
	v_fmac_f32_dpp v17, v17, v25 row_shl:8 row_mask:0xf bank_mask:0xf bound_ctrl:1
	v_mul_f32_dpp v25, v25, v25 row_shl:8 row_mask:0xf bank_mask:0xf
	v_fmac_f32_dpp v2, v2, v10 row_shl:8 row_mask:0xf bank_mask:0xf bound_ctrl:1
	v_mul_f32_dpp v10, v10, v10 row_shl:8 row_mask:0xf bank_mask:0xf
	v_fmac_f32_dpp v3, v3, v11 row_shl:8 row_mask:0xf bank_mask:0xf bound_ctrl:1
	v_mul_f32_dpp v11, v11, v11 row_shl:8 row_mask:0xf bank_mask:0xf
	v_fmac_f32_dpp v4, v4, v12 row_shl:8 row_mask:0xf bank_mask:0xf bound_ctrl:1
	v_mul_f32_dpp v12, v12, v12 row_shl:8 row_mask:0xf bank_mask:0xf
	v_fmac_f32_dpp v5, v5, v13 row_shl:8 row_mask:0xf bank_mask:0xf bound_ctrl:1
	v_mul_f32_dpp v13, v13, v13 row_shl:8 row_mask:0xf bank_mask:0xf
	v_mov_b64_e32 v[172:173], v[146:147]
	v_mov_b64_e32 v[214:215], v[150:151]
	v_mov_b64_e32 v[174:175], v[148:149]
	v_mov_b64_e32 v[216:217], v[152:153]
	v_mov_b64_e32 v[176:177], v[130:131]
	v_mov_b64_e32 v[218:219], v[26:27]
	v_mov_b64_e32 v[178:179], v[132:133]
	v_mov_b64_e32 v[220:221], v[28:29]
	v_mov_b64_e32 v[180:181], v[22:23]
	v_mov_b64_e32 v[222:223], v[14:15]
	v_mov_b64_e32 v[182:183], v[24:25]
	v_mov_b64_e32 v[224:225], v[16:17]
	v_mov_b64_e32 v[192:193], v[10:11]
	v_mov_b64_e32 v[234:235], v[2:3]
	v_mov_b64_e32 v[194:195], v[12:13]
	v_mov_b64_e32 v[236:237], v[4:5]
	s_mov_b64 s[10:11], 0
